# up/res GEMM: first two vmcnt waits of each tile relaxed (epilogue already drained loads; only trailing stores outstanding)
# baseline (speedup 1.0000x reference)
.LBB0_389:
	s_ashr_i32 s29, s28, 31
	s_lshl_b64 s[4:5], s[28:29], 19
	s_add_u32 s30, s12, s4
	s_addc_u32 s31, s13, s5
	s_and_b64 s[4:5], s[40:41], exec
	s_cselect_b32 s29, s31, s43
	s_cselect_b32 vcc_lo, s30, s42
	s_ashr_i32 s37, s36, 31
	s_lshl_b64 s[4:5], s[36:37], 19
	s_add_u32 s34, s17, s4
	s_addc_u32 s35, s70, s5
	s_and_b64 s[4:5], s[40:41], exec
	s_cselect_b32 s37, s35, s39
	s_cselect_b32 vcc_hi, s34, s38
	s_add_u32 s59, s38, 0x100
	v_mov_b32_e32 v74, 0
	s_addc_u32 s72, s39, 0
	s_mov_b32 s73, -2
	s_add_u32 s38, s42, 0x100
	s_addc_u32 s39, s43, 0
	s_add_i32 s4, 0, 0x10000
	s_cmp_eq_u32 s73, 12
	s_cselect_b32 s69, s29, s39
	s_cselect_b32 s68, vcc_lo, s38
	s_cselect_b32 s67, s37, s72
	s_cselect_b32 s66, vcc_hi, s59
	s_add_i32 s6, 0, 0x14000
	v_add_u32_e32 v142, s4, v251
	v_add_u32_e32 v158, s6, v251
	ds_read_b128 v[130:133], v142
	ds_read_b128 v[134:137], v142 offset:1024
	ds_read_b128 v[138:141], v142 offset:2048
	ds_read_b128 v[142:145], v142 offset:3072
	ds_read_b128 v[146:149], v158
	ds_read_b128 v[150:153], v158 offset:1024
	ds_read_b128 v[154:157], v158 offset:2048
	ds_read_b128 v[158:161], v158 offset:3072
	v_lshl_add_u64 v[194:195], s[42:43], 0, v[228:229]
	s_add_i32 m0, s75, 0xc000
	ds_read_b128 v[162:165], v244
	ds_read_b128 v[166:169], v244 offset:1024
	ds_read_b128 v[170:173], v244 offset:2048
	ds_read_b128 v[174:177], v244 offset:3072
	ds_read_b128 v[178:181], v244 offset:4096
	ds_read_b128 v[182:185], v244 offset:5120
	ds_read_b128 v[186:189], v244 offset:6144
	ds_read_b128 v[190:193], v244 offset:7168
	global_load_lds_dwordx4 v[194:195], off
	v_lshl_add_u64 v[194:195], s[42:43], 0, v[230:231]
	s_add_i32 m0, s75, 0xe000
	s_nop 0
	global_load_lds_dwordx4 v[194:195], off
	s_waitcnt vmcnt(16)
	s_waitcnt lgkmcnt(0)
	s_barrier
	s_setprio 1
	s_waitcnt lgkmcnt(0)
	v_mfma_f32_16x16x32_bf16 v[114:117], v[130:133], v[162:165], 0
	v_mfma_f32_16x16x32_bf16 v[122:125], v[138:141], v[162:165], 0
	v_mfma_f32_16x16x32_bf16 v[118:121], v[130:133], v[170:173], 0
	v_mfma_f32_16x16x32_bf16 v[126:129], v[138:141], v[170:173], 0
	v_mfma_f32_16x16x32_bf16 v[54:57], v[130:133], v[178:181], 0
	v_mfma_f32_16x16x32_bf16 v[70:73], v[138:141], v[178:181], 0
	v_mfma_f32_16x16x32_bf16 v[50:53], v[130:133], v[186:189], 0
	v_mfma_f32_16x16x32_bf16 v[66:69], v[138:141], v[186:189], 0
	v_mfma_f32_16x16x32_bf16 v[114:117], v[134:137], v[166:169], v[114:117]
	v_mfma_f32_16x16x32_bf16 v[122:125], v[142:145], v[166:169], v[122:125]
	v_mfma_f32_16x16x32_bf16 v[118:121], v[134:137], v[174:177], v[118:121]
	v_mfma_f32_16x16x32_bf16 v[126:129], v[142:145], v[174:177], v[126:129]
	v_mfma_f32_16x16x32_bf16 v[54:57], v[134:137], v[182:185], v[54:57]
	v_mfma_f32_16x16x32_bf16 v[70:73], v[142:145], v[182:185], v[70:73]
	v_mfma_f32_16x16x32_bf16 v[50:53], v[134:137], v[190:193], v[50:53]
	v_mfma_f32_16x16x32_bf16 v[66:69], v[142:145], v[190:193], v[66:69]
	s_setprio 0
	s_setprio 1
	v_mfma_f32_16x16x32_bf16 v[106:109], v[146:149], v[162:165], 0
	v_mfma_f32_16x16x32_bf16 v[42:45], v[154:157], v[162:165], 0
	v_mfma_f32_16x16x32_bf16 v[110:113], v[146:149], v[170:173], 0
	v_mfma_f32_16x16x32_bf16 v[46:49], v[154:157], v[170:173], 0
	v_mfma_f32_16x16x32_bf16 v[30:33], v[146:149], v[178:181], 0
	v_mfma_f32_16x16x32_bf16 v[14:17], v[154:157], v[178:181], 0
	v_mfma_f32_16x16x32_bf16 v[26:29], v[146:149], v[186:189], 0
	v_mfma_f32_16x16x32_bf16 v[10:13], v[154:157], v[186:189], 0
	v_mfma_f32_16x16x32_bf16 v[106:109], v[150:153], v[166:169], v[106:109]
	v_mfma_f32_16x16x32_bf16 v[42:45], v[158:161], v[166:169], v[42:45]
	v_mfma_f32_16x16x32_bf16 v[110:113], v[150:153], v[174:177], v[110:113]
	v_mfma_f32_16x16x32_bf16 v[46:49], v[158:161], v[174:177], v[46:49]
	v_mfma_f32_16x16x32_bf16 v[30:33], v[150:153], v[182:185], v[30:33]
	v_mfma_f32_16x16x32_bf16 v[14:17], v[158:161], v[182:185], v[14:17]
	v_mfma_f32_16x16x32_bf16 v[26:29], v[150:153], v[190:193], v[26:29]
	s_barrier
	v_mfma_f32_16x16x32_bf16 v[10:13], v[158:161], v[190:193], v[10:13]
	s_setprio 0
	s_add_i32 s4, s4, s74
	v_lshl_add_u64 v[194:195], s[66:67], 0, v[0:1]
	s_mov_b32 m0, s4
	ds_read_b128 v[162:165], v244 offset:16384
	ds_read_b128 v[166:169], v244 offset:17408
	ds_read_b128 v[170:173], v244 offset:18432
	ds_read_b128 v[174:177], v244 offset:19456
	ds_read_b128 v[178:181], v244 offset:20480
	ds_read_b128 v[182:185], v244 offset:21504
	ds_read_b128 v[186:189], v244 offset:22528
	ds_read_b128 v[190:193], v244 offset:23552
	global_load_lds_dwordx4 v[194:195], off
	s_add_i32 m0, s4, 0x2000
	s_add_u32 s4, s66, 0x40000
	v_lshl_add_u64 v[196:197], s[66:67], 0, v[224:225]
	s_addc_u32 s5, s67, 0
	s_add_i32 s6, s6, s74
	global_load_lds_dwordx4 v[196:197], off
	v_lshl_add_u64 v[198:199], s[4:5], 0, v[0:1]
	s_mov_b32 m0, s6
	v_lshl_add_u64 v[200:201], s[68:69], 0, v[222:223]
	global_load_lds_dwordx4 v[198:199], off
	v_lshl_add_u64 v[198:199], s[4:5], 0, v[224:225]
	s_add_i32 m0, s6, 0x2000
	s_nop 0
	global_load_lds_dwordx4 v[198:199], off
	v_lshl_add_u64 v[198:199], s[68:69], 0, v[226:227]
	s_mov_b32 m0, s75
	s_nop 0
	global_load_lds_dwordx4 v[198:199], off
	s_mov_b32 m0, s76
	s_nop 0
	global_load_lds_dwordx4 v[200:201], off
	s_waitcnt vmcnt(16)
	s_waitcnt lgkmcnt(0)
	s_barrier
	s_setprio 1
	s_waitcnt lgkmcnt(0)
	v_mfma_f32_16x16x32_bf16 v[38:41], v[130:133], v[162:165], 0
	v_mfma_f32_16x16x32_bf16 v[62:65], v[138:141], v[162:165], 0
	v_mfma_f32_16x16x32_bf16 v[34:37], v[130:133], v[170:173], 0
	v_mfma_f32_16x16x32_bf16 v[58:61], v[138:141], v[170:173], 0
	v_mfma_f32_16x16x32_bf16 v[102:105], v[130:133], v[178:181], 0
	v_mfma_f32_16x16x32_bf16 v[98:101], v[138:141], v[178:181], 0
	v_mfma_f32_16x16x32_bf16 v[94:97], v[130:133], v[186:189], 0
	v_mfma_f32_16x16x32_bf16 v[90:93], v[138:141], v[186:189], 0
	v_mfma_f32_16x16x32_bf16 v[38:41], v[134:137], v[166:169], v[38:41]
	v_mfma_f32_16x16x32_bf16 v[62:65], v[142:145], v[166:169], v[62:65]
	v_mfma_f32_16x16x32_bf16 v[34:37], v[134:137], v[174:177], v[34:37]
	v_mfma_f32_16x16x32_bf16 v[58:61], v[142:145], v[174:177], v[58:61]
	v_mfma_f32_16x16x32_bf16 v[102:105], v[134:137], v[182:185], v[102:105]
	v_mfma_f32_16x16x32_bf16 v[98:101], v[142:145], v[182:185], v[98:101]
	v_mfma_f32_16x16x32_bf16 v[94:97], v[134:137], v[190:193], v[94:97]
	v_mfma_f32_16x16x32_bf16 v[90:93], v[142:145], v[190:193], v[90:93]
	s_setprio 0
	s_setprio 1
	v_mfma_f32_16x16x32_bf16 v[22:25], v[146:149], v[162:165], 0
	v_mfma_f32_16x16x32_bf16 v[6:9], v[154:157], v[162:165], 0
	v_mfma_f32_16x16x32_bf16 v[18:21], v[146:149], v[170:173], 0
	v_mfma_f32_16x16x32_bf16 v[2:5], v[154:157], v[170:173], 0
	v_mfma_f32_16x16x32_bf16 v[86:89], v[146:149], v[178:181], 0
	v_mfma_f32_16x16x32_bf16 v[82:85], v[154:157], v[178:181], 0
	v_mfma_f32_16x16x32_bf16 v[78:81], v[146:149], v[186:189], 0
	v_mfma_f32_16x16x32_bf16 v[74:77], v[154:157], v[186:189], 0
	v_mfma_f32_16x16x32_bf16 v[22:25], v[150:153], v[166:169], v[22:25]
	v_mfma_f32_16x16x32_bf16 v[6:9], v[158:161], v[166:169], v[6:9]
	v_mfma_f32_16x16x32_bf16 v[18:21], v[150:153], v[174:177], v[18:21]
	v_mfma_f32_16x16x32_bf16 v[2:5], v[158:161], v[174:177], v[2:5]
	v_mfma_f32_16x16x32_bf16 v[86:89], v[150:153], v[182:185], v[86:89]
	v_mfma_f32_16x16x32_bf16 v[82:85], v[158:161], v[182:185], v[82:85]
	v_mfma_f32_16x16x32_bf16 v[78:81], v[150:153], v[190:193], v[78:81]
	s_barrier
	v_mfma_f32_16x16x32_bf16 v[74:77], v[158:161], v[190:193], v[74:77]
	s_setprio 0
	s_add_i32 s6, 0, 0x18000
	s_add_i32 s7, 0, 0x1c000
	v_add_u32_e32 v142, s6, v251
	v_add_u32_e32 v158, s7, v251
	ds_read_b128 v[130:133], v142
	ds_read_b128 v[134:137], v142 offset:1024
	ds_read_b128 v[138:141], v142 offset:2048
	ds_read_b128 v[142:145], v142 offset:3072
	ds_read_b128 v[146:149], v158
	ds_read_b128 v[150:153], v158 offset:1024
	ds_read_b128 v[154:157], v158 offset:2048
	ds_read_b128 v[158:161], v158 offset:3072
	s_add_u32 s4, s68, 0x2000
	s_addc_u32 s5, s69, 0
	s_mov_b32 m0, s77
	v_lshl_add_u64 v[202:203], s[4:5], 0, v[226:227]
	ds_read_b128 v[162:165], v244 offset:32768
	ds_read_b128 v[166:169], v244 offset:33792
	ds_read_b128 v[170:173], v244 offset:34816
	ds_read_b128 v[174:177], v244 offset:35840
	ds_read_b128 v[178:181], v244 offset:36864
	ds_read_b128 v[182:185], v244 offset:37888
	ds_read_b128 v[186:189], v244 offset:38912
	ds_read_b128 v[190:193], v244 offset:39936
	global_load_lds_dwordx4 v[202:203], off
	v_lshl_add_u64 v[202:203], s[4:5], 0, v[222:223]
	s_mov_b32 m0, s78
	s_nop 0
	global_load_lds_dwordx4 v[202:203], off
	s_waitcnt vmcnt(8)
	s_waitcnt lgkmcnt(0)
	s_barrier
	s_setprio 1
	s_waitcnt lgkmcnt(0)
	v_mfma_f32_16x16x32_bf16 v[114:117], v[130:133], v[162:165], v[114:117]
	v_mfma_f32_16x16x32_bf16 v[122:125], v[138:141], v[162:165], v[122:125]
	v_mfma_f32_16x16x32_bf16 v[118:121], v[130:133], v[170:173], v[118:121]
	v_mfma_f32_16x16x32_bf16 v[126:129], v[138:141], v[170:173], v[126:129]
	v_mfma_f32_16x16x32_bf16 v[54:57], v[130:133], v[178:181], v[54:57]
	v_mfma_f32_16x16x32_bf16 v[70:73], v[138:141], v[178:181], v[70:73]
	v_mfma_f32_16x16x32_bf16 v[50:53], v[130:133], v[186:189], v[50:53]
	v_mfma_f32_16x16x32_bf16 v[66:69], v[138:141], v[186:189], v[66:69]
	v_mfma_f32_16x16x32_bf16 v[114:117], v[134:137], v[166:169], v[114:117]
	v_mfma_f32_16x16x32_bf16 v[122:125], v[142:145], v[166:169], v[122:125]
	v_mfma_f32_16x16x32_bf16 v[118:121], v[134:137], v[174:177], v[118:121]
	v_mfma_f32_16x16x32_bf16 v[126:129], v[142:145], v[174:177], v[126:129]
	v_mfma_f32_16x16x32_bf16 v[54:57], v[134:137], v[182:185], v[54:57]
	v_mfma_f32_16x16x32_bf16 v[70:73], v[142:145], v[182:185], v[70:73]
	v_mfma_f32_16x16x32_bf16 v[50:53], v[134:137], v[190:193], v[50:53]
	v_mfma_f32_16x16x32_bf16 v[66:69], v[142:145], v[190:193], v[66:69]
	s_setprio 0
	s_setprio 1
	v_mfma_f32_16x16x32_bf16 v[106:109], v[146:149], v[162:165], v[106:109]
	v_mfma_f32_16x16x32_bf16 v[42:45], v[154:157], v[162:165], v[42:45]
	v_mfma_f32_16x16x32_bf16 v[110:113], v[146:149], v[170:173], v[110:113]
	v_mfma_f32_16x16x32_bf16 v[46:49], v[154:157], v[170:173], v[46:49]
	v_mfma_f32_16x16x32_bf16 v[30:33], v[146:149], v[178:181], v[30:33]
	v_mfma_f32_16x16x32_bf16 v[14:17], v[154:157], v[178:181], v[14:17]
	v_mfma_f32_16x16x32_bf16 v[26:29], v[146:149], v[186:189], v[26:29]
	v_mfma_f32_16x16x32_bf16 v[10:13], v[154:157], v[186:189], v[10:13]
	v_mfma_f32_16x16x32_bf16 v[106:109], v[150:153], v[166:169], v[106:109]
	v_mfma_f32_16x16x32_bf16 v[42:45], v[158:161], v[166:169], v[42:45]
	v_mfma_f32_16x16x32_bf16 v[110:113], v[150:153], v[174:177], v[110:113]
	v_mfma_f32_16x16x32_bf16 v[46:49], v[158:161], v[174:177], v[46:49]
	v_mfma_f32_16x16x32_bf16 v[30:33], v[150:153], v[182:185], v[30:33]
	v_mfma_f32_16x16x32_bf16 v[14:17], v[158:161], v[182:185], v[14:17]
	v_mfma_f32_16x16x32_bf16 v[26:29], v[150:153], v[190:193], v[26:29]
	s_barrier
	v_mfma_f32_16x16x32_bf16 v[10:13], v[158:161], v[190:193], v[10:13]
	s_setprio 0
	s_add_i32 s4, s6, s74
	v_lshl_add_u64 v[194:195], v[194:195], 0, s[82:83]
	s_mov_b32 m0, s4
	ds_read_b128 v[162:165], v244 offset:49152
	ds_read_b128 v[166:169], v244 offset:50176
	ds_read_b128 v[170:173], v244 offset:51200
	ds_read_b128 v[174:177], v244 offset:52224
	ds_read_b128 v[178:181], v244 offset:53248
	ds_read_b128 v[182:185], v244 offset:54272
	ds_read_b128 v[186:189], v244 offset:55296
	ds_read_b128 v[190:193], v244 offset:56320
	global_load_lds_dwordx4 v[194:195], off
	s_add_i32 m0, s4, 0x2000
	s_add_u32 s4, s66, 0x40080
	v_lshl_add_u64 v[194:195], v[196:197], 0, s[82:83]
	s_addc_u32 s5, s67, 0
	s_add_i32 s6, s7, s74
	global_load_lds_dwordx4 v[194:195], off
	v_lshl_add_u64 v[194:195], s[4:5], 0, v[0:1]
	s_mov_b32 m0, s6
	s_nop 0
	global_load_lds_dwordx4 v[194:195], off
	v_lshl_add_u64 v[194:195], s[4:5], 0, v[224:225]
	s_add_i32 m0, s6, 0x2000
	s_nop 0
	global_load_lds_dwordx4 v[194:195], off
	v_lshl_add_u64 v[194:195], v[198:199], 0, s[82:83]
	s_mov_b32 m0, s94
	s_nop 0
	global_load_lds_dwordx4 v[194:195], off
	v_lshl_add_u64 v[194:195], v[200:201], 0, s[82:83]
	s_mov_b32 m0, s95
	s_nop 0
	global_load_lds_dwordx4 v[194:195], off
	s_waitcnt vmcnt(8)
	s_waitcnt lgkmcnt(0)
	s_barrier
	s_setprio 1
	s_waitcnt lgkmcnt(0)
	v_mfma_f32_16x16x32_bf16 v[38:41], v[130:133], v[162:165], v[38:41]
	v_mfma_f32_16x16x32_bf16 v[62:65], v[138:141], v[162:165], v[62:65]
	v_mfma_f32_16x16x32_bf16 v[34:37], v[130:133], v[170:173], v[34:37]
	v_mfma_f32_16x16x32_bf16 v[58:61], v[138:141], v[170:173], v[58:61]
	v_mfma_f32_16x16x32_bf16 v[102:105], v[130:133], v[178:181], v[102:105]
	v_mfma_f32_16x16x32_bf16 v[98:101], v[138:141], v[178:181], v[98:101]
	v_mfma_f32_16x16x32_bf16 v[94:97], v[130:133], v[186:189], v[94:97]
	v_mfma_f32_16x16x32_bf16 v[90:93], v[138:141], v[186:189], v[90:93]
	v_mfma_f32_16x16x32_bf16 v[38:41], v[134:137], v[166:169], v[38:41]
	v_mfma_f32_16x16x32_bf16 v[62:65], v[142:145], v[166:169], v[62:65]
	v_mfma_f32_16x16x32_bf16 v[34:37], v[134:137], v[174:177], v[34:37]
	v_mfma_f32_16x16x32_bf16 v[58:61], v[142:145], v[174:177], v[58:61]
	v_mfma_f32_16x16x32_bf16 v[102:105], v[134:137], v[182:185], v[102:105]
	v_mfma_f32_16x16x32_bf16 v[98:101], v[142:145], v[182:185], v[98:101]
	v_mfma_f32_16x16x32_bf16 v[94:97], v[134:137], v[190:193], v[94:97]
	v_mfma_f32_16x16x32_bf16 v[90:93], v[142:145], v[190:193], v[90:93]
	s_setprio 0
	s_setprio 1
	v_mfma_f32_16x16x32_bf16 v[22:25], v[146:149], v[162:165], v[22:25]
	v_mfma_f32_16x16x32_bf16 v[6:9], v[154:157], v[162:165], v[6:9]
	v_mfma_f32_16x16x32_bf16 v[18:21], v[146:149], v[170:173], v[18:21]
	v_mfma_f32_16x16x32_bf16 v[2:5], v[154:157], v[170:173], v[2:5]
	v_mfma_f32_16x16x32_bf16 v[86:89], v[146:149], v[178:181], v[86:89]
	v_mfma_f32_16x16x32_bf16 v[82:85], v[154:157], v[178:181], v[82:85]
	v_mfma_f32_16x16x32_bf16 v[78:81], v[146:149], v[186:189], v[78:81]
	v_mfma_f32_16x16x32_bf16 v[74:77], v[154:157], v[186:189], v[74:77]
	v_mfma_f32_16x16x32_bf16 v[22:25], v[150:153], v[166:169], v[22:25]
	v_mfma_f32_16x16x32_bf16 v[6:9], v[158:161], v[166:169], v[6:9]
	v_mfma_f32_16x16x32_bf16 v[18:21], v[150:153], v[174:177], v[18:21]
	v_mfma_f32_16x16x32_bf16 v[2:5], v[158:161], v[174:177], v[2:5]
	v_mfma_f32_16x16x32_bf16 v[86:89], v[150:153], v[182:185], v[86:89]
	v_mfma_f32_16x16x32_bf16 v[82:85], v[158:161], v[182:185], v[82:85]
	v_mfma_f32_16x16x32_bf16 v[78:81], v[150:153], v[190:193], v[78:81]
	s_barrier
	v_mfma_f32_16x16x32_bf16 v[74:77], v[158:161], v[190:193], v[74:77]
	s_setprio 0
	s_add_i32 s73, s73, 2
	s_add_u32 s59, s59, 0x100
	s_addc_u32 s72, s72, 0
	s_cmp_gt_u32 s73, 13
	s_mov_b64 s[42:43], s[38:39]

.LBB0_451:
	s_add_u32 s30, s30, 0x80
	s_addc_u32 s31, s31, 0
	s_add_u32 s42, s34, 0x100
	v_mov_b32_e32 v2, 0
	s_addc_u32 s43, s35, 0
	s_mov_b32 s34, 0
	s_waitcnt lgkmcnt(0)
	s_add_i32 s59, s34, 2
	s_add_u32 s4, s30, 0x80
	s_addc_u32 s5, s31, 0
	s_add_i32 s6, 0, 0x10000
	s_cmp_eq_u32 s53, s34
	s_cselect_b32 s35, s27, s5
	s_cselect_b32 s34, s26, s4
	s_cselect_b32 s5, s29, s43
	s_cselect_b32 s4, s28, s42
	s_add_i32 s7, 0, 0x14000
	v_add_u32_e32 v142, s6, v184
	v_add_u32_e32 v168, s7, v184
	ds_read_b128 v[130:133], v142
	ds_read_b128 v[134:137], v142 offset:1024
	ds_read_b128 v[138:141], v142 offset:2048
	ds_read_b128 v[142:145], v142 offset:3072
	ds_read_b128 v[146:149], v168
	ds_read_b128 v[150:153], v168 offset:1024
	ds_read_b128 v[154:157], v168 offset:2048
	ds_read_b128 v[168:171], v168 offset:3072
	v_lshl_add_u64 v[180:181], s[30:31], 0, v[164:165]
	s_add_i32 m0, s38, 0xc000
	ds_read_b128 v[172:175], v187
	ds_read_b128 v[176:179], v187 offset:1024
	ds_read_b128 v[188:191], v187 offset:2048
	ds_read_b128 v[192:195], v187 offset:3072
	ds_read_b128 v[196:199], v187 offset:4096
	ds_read_b128 v[200:203], v187 offset:5120
	ds_read_b128 v[204:207], v187 offset:6144
	ds_read_b128 v[222:225], v187 offset:7168
	global_load_lds_dwordx4 v[180:181], off
	v_lshl_add_u64 v[180:181], s[30:31], 0, v[166:167]
	s_add_i32 m0, s38, 0xe000
	s_nop 0
	global_load_lds_dwordx4 v[180:181], off
	s_waitcnt vmcnt(20)
	s_waitcnt lgkmcnt(0)
	s_barrier
	s_setprio 1
	s_waitcnt lgkmcnt(0)
	v_mfma_f32_16x16x32_bf16 v[126:129], v[130:133], v[172:175], 0
	v_mfma_f32_16x16x32_bf16 v[122:125], v[138:141], v[172:175], 0
	v_mfma_f32_16x16x32_bf16 v[110:113], v[130:133], v[188:191], 0
	v_mfma_f32_16x16x32_bf16 v[106:109], v[138:141], v[188:191], 0
	v_mfma_f32_16x16x32_bf16 v[98:101], v[130:133], v[196:199], 0
	v_mfma_f32_16x16x32_bf16 v[90:93], v[138:141], v[196:199], 0
	v_mfma_f32_16x16x32_bf16 v[82:85], v[130:133], v[204:207], 0
	v_mfma_f32_16x16x32_bf16 v[74:77], v[138:141], v[204:207], 0
	v_mfma_f32_16x16x32_bf16 v[126:129], v[134:137], v[176:179], v[126:129]
	v_mfma_f32_16x16x32_bf16 v[122:125], v[142:145], v[176:179], v[122:125]
	v_mfma_f32_16x16x32_bf16 v[110:113], v[134:137], v[192:195], v[110:113]
	v_mfma_f32_16x16x32_bf16 v[106:109], v[142:145], v[192:195], v[106:109]
	v_mfma_f32_16x16x32_bf16 v[98:101], v[134:137], v[200:203], v[98:101]
	v_mfma_f32_16x16x32_bf16 v[90:93], v[142:145], v[200:203], v[90:93]
	v_mfma_f32_16x16x32_bf16 v[82:85], v[134:137], v[222:225], v[82:85]
	v_mfma_f32_16x16x32_bf16 v[74:77], v[142:145], v[222:225], v[74:77]
	s_setprio 0
	s_setprio 1
	v_mfma_f32_16x16x32_bf16 v[118:121], v[146:149], v[172:175], 0
	v_mfma_f32_16x16x32_bf16 v[114:117], v[154:157], v[172:175], 0
	v_mfma_f32_16x16x32_bf16 v[102:105], v[146:149], v[188:191], 0
	v_mfma_f32_16x16x32_bf16 v[94:97], v[154:157], v[188:191], 0
	v_mfma_f32_16x16x32_bf16 v[86:89], v[146:149], v[196:199], 0
	v_mfma_f32_16x16x32_bf16 v[78:81], v[154:157], v[196:199], 0
	v_mfma_f32_16x16x32_bf16 v[70:73], v[146:149], v[204:207], 0
	v_mfma_f32_16x16x32_bf16 v[66:69], v[154:157], v[204:207], 0
	v_mfma_f32_16x16x32_bf16 v[118:121], v[150:153], v[176:179], v[118:121]
	v_mfma_f32_16x16x32_bf16 v[114:117], v[168:171], v[176:179], v[114:117]
	v_mfma_f32_16x16x32_bf16 v[102:105], v[150:153], v[192:195], v[102:105]
	v_mfma_f32_16x16x32_bf16 v[94:97], v[168:171], v[192:195], v[94:97]
	v_mfma_f32_16x16x32_bf16 v[86:89], v[150:153], v[200:203], v[86:89]
	v_mfma_f32_16x16x32_bf16 v[78:81], v[168:171], v[200:203], v[78:81]
	v_mfma_f32_16x16x32_bf16 v[70:73], v[150:153], v[222:225], v[70:73]
	s_barrier
	v_mfma_f32_16x16x32_bf16 v[66:69], v[168:171], v[222:225], v[66:69]
	s_setprio 0
	s_add_i32 s6, s6, s37
	v_lshl_add_u64 v[180:181], s[4:5], 0, v[0:1]
	s_mov_b32 m0, s6
	ds_read_b128 v[172:175], v187 offset:16384
	ds_read_b128 v[176:179], v187 offset:17408
	ds_read_b128 v[188:191], v187 offset:18432
	ds_read_b128 v[192:195], v187 offset:19456
	ds_read_b128 v[196:199], v187 offset:20480
	ds_read_b128 v[200:203], v187 offset:21504
	ds_read_b128 v[204:207], v187 offset:22528
	ds_read_b128 v[222:225], v187 offset:23552
	global_load_lds_dwordx4 v[180:181], off
	s_add_i32 m0, s6, 0x2000
	v_lshl_add_u64 v[208:209], s[4:5], 0, v[160:161]
	s_add_u32 s4, s4, s84
	s_addc_u32 s5, s5, 0
	s_add_i32 s6, s7, s37
	global_load_lds_dwordx4 v[208:209], off
	v_lshl_add_u64 v[226:227], s[4:5], 0, v[0:1]
	s_mov_b32 m0, s6
	v_lshl_add_u64 v[228:229], s[4:5], 0, v[160:161]
	global_load_lds_dwordx4 v[226:227], off
	s_add_i32 m0, s6, 0x2000
	v_lshl_add_u64 v[230:231], s[34:35], 0, v[162:163]
	global_load_lds_dwordx4 v[228:229], off
	s_mov_b32 m0, s38
	v_lshl_add_u64 v[232:233], s[34:35], 0, v[158:159]
	global_load_lds_dwordx4 v[230:231], off
	s_mov_b32 m0, s39
	s_nop 0
	global_load_lds_dwordx4 v[232:233], off
	s_waitcnt vmcnt(20)
	s_waitcnt lgkmcnt(0)
	s_barrier
	s_setprio 1
	s_waitcnt lgkmcnt(0)
	v_mfma_f32_16x16x32_bf16 v[62:65], v[130:133], v[172:175], 0
	v_mfma_f32_16x16x32_bf16 v[58:61], v[138:141], v[172:175], 0
	v_mfma_f32_16x16x32_bf16 v[46:49], v[130:133], v[188:191], 0
	v_mfma_f32_16x16x32_bf16 v[42:45], v[138:141], v[188:191], 0
	v_mfma_f32_16x16x32_bf16 v[34:37], v[130:133], v[196:199], 0
	v_mfma_f32_16x16x32_bf16 v[26:29], v[138:141], v[196:199], 0
	v_mfma_f32_16x16x32_bf16 v[18:21], v[130:133], v[204:207], 0
	v_mfma_f32_16x16x32_bf16 v[10:13], v[138:141], v[204:207], 0
	v_mfma_f32_16x16x32_bf16 v[62:65], v[134:137], v[176:179], v[62:65]
	v_mfma_f32_16x16x32_bf16 v[58:61], v[142:145], v[176:179], v[58:61]
	v_mfma_f32_16x16x32_bf16 v[46:49], v[134:137], v[192:195], v[46:49]
	v_mfma_f32_16x16x32_bf16 v[42:45], v[142:145], v[192:195], v[42:45]
	v_mfma_f32_16x16x32_bf16 v[34:37], v[134:137], v[200:203], v[34:37]
	v_mfma_f32_16x16x32_bf16 v[26:29], v[142:145], v[200:203], v[26:29]
	v_mfma_f32_16x16x32_bf16 v[18:21], v[134:137], v[222:225], v[18:21]
	v_mfma_f32_16x16x32_bf16 v[10:13], v[142:145], v[222:225], v[10:13]
	s_setprio 0
	s_setprio 1
	v_mfma_f32_16x16x32_bf16 v[54:57], v[146:149], v[172:175], 0
	v_mfma_f32_16x16x32_bf16 v[50:53], v[154:157], v[172:175], 0
	v_mfma_f32_16x16x32_bf16 v[38:41], v[146:149], v[188:191], 0
	v_mfma_f32_16x16x32_bf16 v[30:33], v[154:157], v[188:191], 0
	v_mfma_f32_16x16x32_bf16 v[22:25], v[146:149], v[196:199], 0
	v_mfma_f32_16x16x32_bf16 v[14:17], v[154:157], v[196:199], 0
	v_mfma_f32_16x16x32_bf16 v[6:9], v[146:149], v[204:207], 0
	v_mfma_f32_16x16x32_bf16 v[2:5], v[154:157], v[204:207], 0
	v_mfma_f32_16x16x32_bf16 v[54:57], v[150:153], v[176:179], v[54:57]
	v_mfma_f32_16x16x32_bf16 v[50:53], v[168:171], v[176:179], v[50:53]
	v_mfma_f32_16x16x32_bf16 v[38:41], v[150:153], v[192:195], v[38:41]
	v_mfma_f32_16x16x32_bf16 v[30:33], v[168:171], v[192:195], v[30:33]
	v_mfma_f32_16x16x32_bf16 v[22:25], v[150:153], v[200:203], v[22:25]
	v_mfma_f32_16x16x32_bf16 v[14:17], v[168:171], v[200:203], v[14:17]
	v_mfma_f32_16x16x32_bf16 v[6:9], v[150:153], v[222:225], v[6:9]
	s_barrier
	v_mfma_f32_16x16x32_bf16 v[2:5], v[168:171], v[222:225], v[2:5]
	s_setprio 0
	s_add_i32 s6, 0, 0x18000
	s_add_i32 s7, 0, 0x1c000
	v_add_u32_e32 v142, s6, v184
	v_add_u32_e32 v168, s7, v184
	ds_read_b128 v[130:133], v142
	ds_read_b128 v[134:137], v142 offset:1024
	ds_read_b128 v[138:141], v142 offset:2048
	ds_read_b128 v[142:145], v142 offset:3072
	ds_read_b128 v[146:149], v168
	ds_read_b128 v[150:153], v168 offset:1024
	ds_read_b128 v[154:157], v168 offset:2048
	ds_read_b128 v[168:171], v168 offset:3072
	s_add_u32 s4, s34, s84
	s_addc_u32 s5, s35, 0
	s_mov_b32 m0, s45
	v_lshl_add_u64 v[234:235], s[4:5], 0, v[162:163]
	ds_read_b128 v[172:175], v187 offset:32768
	ds_read_b128 v[176:179], v187 offset:33792
	ds_read_b128 v[188:191], v187 offset:34816
	ds_read_b128 v[192:195], v187 offset:35840
	ds_read_b128 v[196:199], v187 offset:36864
	ds_read_b128 v[200:203], v187 offset:37888
	ds_read_b128 v[204:207], v187 offset:38912
	ds_read_b128 v[222:225], v187 offset:39936
	global_load_lds_dwordx4 v[234:235], off
	v_lshl_add_u64 v[234:235], s[4:5], 0, v[158:159]
	s_mov_b32 m0, s46
	s_nop 0
	global_load_lds_dwordx4 v[234:235], off
	s_waitcnt vmcnt(8)
	s_waitcnt lgkmcnt(0)
	s_barrier
	s_setprio 1
	s_waitcnt lgkmcnt(0)
	v_mfma_f32_16x16x32_bf16 v[126:129], v[130:133], v[172:175], v[126:129]
	v_mfma_f32_16x16x32_bf16 v[122:125], v[138:141], v[172:175], v[122:125]
	v_mfma_f32_16x16x32_bf16 v[110:113], v[130:133], v[188:191], v[110:113]
	v_mfma_f32_16x16x32_bf16 v[106:109], v[138:141], v[188:191], v[106:109]
	v_mfma_f32_16x16x32_bf16 v[98:101], v[130:133], v[196:199], v[98:101]
	v_mfma_f32_16x16x32_bf16 v[90:93], v[138:141], v[196:199], v[90:93]
	v_mfma_f32_16x16x32_bf16 v[82:85], v[130:133], v[204:207], v[82:85]
	v_mfma_f32_16x16x32_bf16 v[74:77], v[138:141], v[204:207], v[74:77]
	v_mfma_f32_16x16x32_bf16 v[126:129], v[134:137], v[176:179], v[126:129]
	v_mfma_f32_16x16x32_bf16 v[122:125], v[142:145], v[176:179], v[122:125]
	v_mfma_f32_16x16x32_bf16 v[110:113], v[134:137], v[192:195], v[110:113]
	v_mfma_f32_16x16x32_bf16 v[106:109], v[142:145], v[192:195], v[106:109]
	v_mfma_f32_16x16x32_bf16 v[98:101], v[134:137], v[200:203], v[98:101]
	v_mfma_f32_16x16x32_bf16 v[90:93], v[142:145], v[200:203], v[90:93]
	v_mfma_f32_16x16x32_bf16 v[82:85], v[134:137], v[222:225], v[82:85]
	v_mfma_f32_16x16x32_bf16 v[74:77], v[142:145], v[222:225], v[74:77]
	s_setprio 0
	s_setprio 1
	v_mfma_f32_16x16x32_bf16 v[118:121], v[146:149], v[172:175], v[118:121]
	v_mfma_f32_16x16x32_bf16 v[114:117], v[154:157], v[172:175], v[114:117]
	v_mfma_f32_16x16x32_bf16 v[102:105], v[146:149], v[188:191], v[102:105]
	v_mfma_f32_16x16x32_bf16 v[94:97], v[154:157], v[188:191], v[94:97]
	v_mfma_f32_16x16x32_bf16 v[86:89], v[146:149], v[196:199], v[86:89]
	v_mfma_f32_16x16x32_bf16 v[78:81], v[154:157], v[196:199], v[78:81]
	v_mfma_f32_16x16x32_bf16 v[70:73], v[146:149], v[204:207], v[70:73]
	v_mfma_f32_16x16x32_bf16 v[66:69], v[154:157], v[204:207], v[66:69]
	v_mfma_f32_16x16x32_bf16 v[118:121], v[150:153], v[176:179], v[118:121]
	v_mfma_f32_16x16x32_bf16 v[114:117], v[168:171], v[176:179], v[114:117]
	v_mfma_f32_16x16x32_bf16 v[102:105], v[150:153], v[192:195], v[102:105]
	v_mfma_f32_16x16x32_bf16 v[94:97], v[168:171], v[192:195], v[94:97]
	v_mfma_f32_16x16x32_bf16 v[86:89], v[150:153], v[200:203], v[86:89]
	v_mfma_f32_16x16x32_bf16 v[78:81], v[168:171], v[200:203], v[78:81]
	v_mfma_f32_16x16x32_bf16 v[70:73], v[150:153], v[222:225], v[70:73]
	s_barrier
	v_mfma_f32_16x16x32_bf16 v[66:69], v[168:171], v[222:225], v[66:69]
	s_setprio 0
	s_add_i32 s4, s6, s37
	v_lshl_add_u64 v[180:181], v[180:181], 0, s[82:83]
	s_mov_b32 m0, s4
	ds_read_b128 v[172:175], v187 offset:49152
	ds_read_b128 v[176:179], v187 offset:50176
	ds_read_b128 v[188:191], v187 offset:51200
	ds_read_b128 v[192:195], v187 offset:52224
	ds_read_b128 v[196:199], v187 offset:53248
	ds_read_b128 v[200:203], v187 offset:54272
	ds_read_b128 v[204:207], v187 offset:55296
	ds_read_b128 v[222:225], v187 offset:56320
	global_load_lds_dwordx4 v[180:181], off
	v_lshl_add_u64 v[180:181], v[208:209], 0, s[82:83]
	s_add_i32 m0, s4, 0x2000
	s_add_i32 s4, s7, s37
	global_load_lds_dwordx4 v[180:181], off
	v_lshl_add_u64 v[180:181], v[226:227], 0, s[82:83]
	s_mov_b32 m0, s4
	s_nop 0
	global_load_lds_dwordx4 v[180:181], off
	v_lshl_add_u64 v[180:181], v[228:229], 0, s[82:83]
	s_add_i32 m0, s4, 0x2000
	s_nop 0
	global_load_lds_dwordx4 v[180:181], off
	v_lshl_add_u64 v[180:181], v[230:231], 0, s[82:83]
	s_mov_b32 m0, s51
	s_nop 0
	global_load_lds_dwordx4 v[180:181], off
	v_lshl_add_u64 v[180:181], v[232:233], 0, s[82:83]
	s_mov_b32 m0, s52
	s_nop 0
	global_load_lds_dwordx4 v[180:181], off
	s_waitcnt vmcnt(8)
	s_waitcnt lgkmcnt(0)
	s_barrier
	s_setprio 1
	s_waitcnt lgkmcnt(0)
	v_mfma_f32_16x16x32_bf16 v[62:65], v[130:133], v[172:175], v[62:65]
	v_mfma_f32_16x16x32_bf16 v[58:61], v[138:141], v[172:175], v[58:61]
	v_mfma_f32_16x16x32_bf16 v[46:49], v[130:133], v[188:191], v[46:49]
	v_mfma_f32_16x16x32_bf16 v[42:45], v[138:141], v[188:191], v[42:45]
	v_mfma_f32_16x16x32_bf16 v[34:37], v[130:133], v[196:199], v[34:37]
	v_mfma_f32_16x16x32_bf16 v[26:29], v[138:141], v[196:199], v[26:29]
	v_mfma_f32_16x16x32_bf16 v[18:21], v[130:133], v[204:207], v[18:21]
	v_mfma_f32_16x16x32_bf16 v[10:13], v[138:141], v[204:207], v[10:13]
	v_mfma_f32_16x16x32_bf16 v[62:65], v[134:137], v[176:179], v[62:65]
	v_mfma_f32_16x16x32_bf16 v[58:61], v[142:145], v[176:179], v[58:61]
	v_mfma_f32_16x16x32_bf16 v[46:49], v[134:137], v[192:195], v[46:49]
	v_mfma_f32_16x16x32_bf16 v[42:45], v[142:145], v[192:195], v[42:45]
	v_mfma_f32_16x16x32_bf16 v[34:37], v[134:137], v[200:203], v[34:37]
	v_mfma_f32_16x16x32_bf16 v[26:29], v[142:145], v[200:203], v[26:29]
	v_mfma_f32_16x16x32_bf16 v[18:21], v[134:137], v[222:225], v[18:21]
	v_mfma_f32_16x16x32_bf16 v[10:13], v[142:145], v[222:225], v[10:13]
	s_setprio 0
	s_setprio 1
	v_mfma_f32_16x16x32_bf16 v[54:57], v[146:149], v[172:175], v[54:57]
	v_mfma_f32_16x16x32_bf16 v[50:53], v[154:157], v[172:175], v[50:53]
	v_mfma_f32_16x16x32_bf16 v[38:41], v[146:149], v[188:191], v[38:41]
	v_mfma_f32_16x16x32_bf16 v[30:33], v[154:157], v[188:191], v[30:33]
	v_mfma_f32_16x16x32_bf16 v[22:25], v[146:149], v[196:199], v[22:25]
	v_mfma_f32_16x16x32_bf16 v[14:17], v[154:157], v[196:199], v[14:17]
	v_mfma_f32_16x16x32_bf16 v[6:9], v[146:149], v[204:207], v[6:9]
	v_mfma_f32_16x16x32_bf16 v[2:5], v[154:157], v[204:207], v[2:5]
	v_mfma_f32_16x16x32_bf16 v[54:57], v[150:153], v[176:179], v[54:57]
	v_mfma_f32_16x16x32_bf16 v[50:53], v[168:171], v[176:179], v[50:53]
	v_mfma_f32_16x16x32_bf16 v[38:41], v[150:153], v[192:195], v[38:41]
	v_mfma_f32_16x16x32_bf16 v[30:33], v[168:171], v[192:195], v[30:33]
	v_mfma_f32_16x16x32_bf16 v[22:25], v[150:153], v[200:203], v[22:25]
	v_mfma_f32_16x16x32_bf16 v[14:17], v[168:171], v[200:203], v[14:17]
	v_mfma_f32_16x16x32_bf16 v[6:9], v[150:153], v[222:225], v[6:9]
	s_barrier
	v_mfma_f32_16x16x32_bf16 v[2:5], v[168:171], v[222:225], v[2:5]
	s_setprio 0
	s_add_u32 s30, s30, 0x100
	s_addc_u32 s31, s31, 0
	s_add_u32 s42, s42, 0x100
	s_addc_u32 s43, s43, 0
	s_cmp_ge_u32 s59, s48
	s_mov_b32 s34, s59
